# gate-up SwiGLU epilogue rewritten by hand: packed f32 VALU, in-place, no serial chain
# speedup vs baseline: 1.0078x; 1.0078x over previous
; __device__ __forceinline__ unsigned cvt_pk_bf16(float lo, float hi) { unsigned r; asm volatile("v_cvt_pk_bf16_f32 %0, %1, %2" : "=v"(r) : "v"(lo), "v"(hi)); return r; }
;     __device__ __forceinline__ void operator()(const f32x4 (&acc)[2][2][4][2], const Unit& u, int wr, int wc, int fr, int fq) const {
;         const int row0 = u.pm * BM + wr * 64 + fr, col0 = u.pn * HALF + wc * 32 + 8 * fq;
;         float rsv[2][4];
; #pragma unroll
;         for (int ai = 0; ai < 2; ++ai)
; #pragma unroll
;             for (int m = 0; m < 4; ++m) rsv[ai][m] = rsT[u.ui * 256 + ai * HALF + wr * 64 + m * 16 + fr];
; #pragma unroll
;         for (int ai = 0; ai < 2; ++ai)
; #pragma unroll
;             for (int m = 0; m < 4; ++m) {
;                 bf16_t* rowp = O + (size_t)(row0 + ai * HALF + m * 16) * FF + col0;
;                 const float rs = rsv[ai][m];
;                 float a[8];
; #pragma unroll
;                 for (int n = 0; n < 2; ++n)
; #pragma unroll
;                     for (int j = 0; j < 4; ++j) { const float g = acc[ai][0][m][n][j] * rs, up = acc[ai][1][m][n][j] * rs;
;                         const float sg = g * __builtin_amdgcn_rcpf(1.0f + __builtin_amdgcn_exp2f(-1.4426950408889634f * g)); a[n * 4 + j] = sg * up; }
;                 u32x4 w; w.x = cvt_pk_bf16(a[0], a[1]); w.y = cvt_pk_bf16(a[2], a[3]); w.z = cvt_pk_bf16(a[4], a[5]); w.w = cvt_pk_bf16(a[6], a[7]);
;                 *(u32x4*)rowp = w;
;             }
.LBB0_2281:
	v_lshl_add_u32 v140, s68, 10, v154
	ds_read2_b32 v[148:149], v140 offset1:16
	ds_read2_b32 v[146:147], v140 offset0:32 offset1:48
	ds_read2_b32 v[144:145], v140 offset0:128 offset1:144
	ds_read2_b32 v[140:141], v140 offset0:160 offset1:176
	v_lshl_or_b32 v150, s17, 7, v155
	v_lshl_add_u32 v157, s16, 8, v152
	v_ashrrev_i32_e32 v151, 31, v150
	v_mov_b64_e32 v[142:143], s[84:85]
	s_andn2_b64 vcc, exec, s[2:3]
	v_lshlrev_b64 v[150:151], 1, v[150:151]
	v_mov_b32_e32 v176, 1.0
	v_mov_b32_e32 v177, 0xbfb8aa3b
	v_lshl_add_u64 v[142:143], v[142:143], 0, v[150:151]
	s_waitcnt lgkmcnt(0)
	v_pk_mul_f32 v[178:179], v[148:149], v[176:177] op_sel:[0,1] op_sel_hi:[1,1]
	v_pk_mul_f32 v[180:181], v[146:147], v[176:177] op_sel:[0,1] op_sel_hi:[1,1]
	v_pk_mul_f32 v[182:183], v[144:145], v[176:177] op_sel:[0,1] op_sel_hi:[1,1]
	v_pk_mul_f32 v[184:185], v[140:141], v[176:177] op_sel:[0,1] op_sel_hi:[1,1]
	v_pk_mul_f32 v[186:187], v[148:149], v[148:149]
	v_pk_mul_f32 v[188:189], v[146:147], v[146:147]
	v_pk_mul_f32 v[190:191], v[144:145], v[144:145]
	v_pk_mul_f32 v[192:193], v[140:141], v[140:141]
	v_mad_i64_i32 v[194:195], s[16:17], v157, s81, v[142:143]
	v_pk_mul_f32 v[122:123], v[126:127], v[122:123]
	v_pk_mul_f32 v[124:125], v[128:129], v[124:125]
	v_pk_mul_f32 v[114:115], v[118:119], v[114:115]
	v_pk_mul_f32 v[116:117], v[120:121], v[116:117]
	v_pk_mul_f32 v[126:127], v[126:127], v[178:179] op_sel_hi:[1,0]
	v_pk_mul_f32 v[128:129], v[128:129], v[178:179] op_sel_hi:[1,0]
	v_pk_mul_f32 v[118:119], v[118:119], v[178:179] op_sel_hi:[1,0]
	v_pk_mul_f32 v[120:121], v[120:121], v[178:179] op_sel_hi:[1,0]
	v_exp_f32_e32 v126, v126
	v_exp_f32_e32 v127, v127
	v_exp_f32_e32 v128, v128
	v_exp_f32_e32 v129, v129
	v_exp_f32_e32 v118, v118
	v_exp_f32_e32 v119, v119
	v_exp_f32_e32 v120, v120
	v_exp_f32_e32 v121, v121
	v_pk_add_f32 v[126:127], v[126:127], v[176:177] op_sel_hi:[1,0]
	v_pk_add_f32 v[128:129], v[128:129], v[176:177] op_sel_hi:[1,0]
	v_pk_add_f32 v[118:119], v[118:119], v[176:177] op_sel_hi:[1,0]
	v_pk_add_f32 v[120:121], v[120:121], v[176:177] op_sel_hi:[1,0]
	v_rcp_f32_e32 v126, v126
	v_rcp_f32_e32 v127, v127
	v_rcp_f32_e32 v128, v128
	v_rcp_f32_e32 v129, v129
	v_rcp_f32_e32 v118, v118
	v_rcp_f32_e32 v119, v119
	v_rcp_f32_e32 v120, v120
	v_rcp_f32_e32 v121, v121
	v_pk_mul_f32 v[122:123], v[122:123], v[186:187] op_sel_hi:[1,0]
	v_pk_mul_f32 v[124:125], v[124:125], v[186:187] op_sel_hi:[1,0]
	v_pk_mul_f32 v[114:115], v[114:115], v[186:187] op_sel_hi:[1,0]
	v_pk_mul_f32 v[116:117], v[116:117], v[186:187] op_sel_hi:[1,0]
	v_pk_mul_f32 v[122:123], v[122:123], v[126:127]
	v_pk_mul_f32 v[124:125], v[124:125], v[128:129]
	v_pk_mul_f32 v[114:115], v[114:115], v[118:119]
	v_pk_mul_f32 v[116:117], v[116:117], v[120:121]
	v_cvt_pk_bf16_f32 v126, v122, v123
	v_cvt_pk_bf16_f32 v127, v124, v125
	v_cvt_pk_bf16_f32 v128, v114, v115
	v_cvt_pk_bf16_f32 v129, v116, v117
	global_store_dwordx4 v[194:195], v[126:129], off
	v_add_u32_e32 v196, 0x10, v157
	v_mad_i64_i32 v[196:197], s[16:17], v196, s81, v[142:143]
	v_pk_mul_f32 v[106:107], v[110:111], v[106:107]
	v_pk_mul_f32 v[108:109], v[112:113], v[108:109]
	v_pk_mul_f32 v[98:99], v[102:103], v[98:99]
	v_pk_mul_f32 v[100:101], v[104:105], v[100:101]
	v_pk_mul_f32 v[110:111], v[110:111], v[178:179] op_sel:[0,1] op_sel_hi:[1,1]
	v_pk_mul_f32 v[112:113], v[112:113], v[178:179] op_sel:[0,1] op_sel_hi:[1,1]
	v_pk_mul_f32 v[102:103], v[102:103], v[178:179] op_sel:[0,1] op_sel_hi:[1,1]
	v_pk_mul_f32 v[104:105], v[104:105], v[178:179] op_sel:[0,1] op_sel_hi:[1,1]
	v_exp_f32_e32 v110, v110
	v_exp_f32_e32 v111, v111
	v_exp_f32_e32 v112, v112
	v_exp_f32_e32 v113, v113
	v_exp_f32_e32 v102, v102
	v_exp_f32_e32 v103, v103
	v_exp_f32_e32 v104, v104
	v_exp_f32_e32 v105, v105
	v_pk_add_f32 v[110:111], v[110:111], v[176:177] op_sel_hi:[1,0]
	v_pk_add_f32 v[112:113], v[112:113], v[176:177] op_sel_hi:[1,0]
	v_pk_add_f32 v[102:103], v[102:103], v[176:177] op_sel_hi:[1,0]
	v_pk_add_f32 v[104:105], v[104:105], v[176:177] op_sel_hi:[1,0]
	v_rcp_f32_e32 v110, v110
	v_rcp_f32_e32 v111, v111
	v_rcp_f32_e32 v112, v112
	v_rcp_f32_e32 v113, v113
	v_rcp_f32_e32 v102, v102
	v_rcp_f32_e32 v103, v103
	v_rcp_f32_e32 v104, v104
	v_rcp_f32_e32 v105, v105
	v_pk_mul_f32 v[106:107], v[106:107], v[186:187] op_sel:[0,1] op_sel_hi:[1,1]
	v_pk_mul_f32 v[108:109], v[108:109], v[186:187] op_sel:[0,1] op_sel_hi:[1,1]
	v_pk_mul_f32 v[98:99], v[98:99], v[186:187] op_sel:[0,1] op_sel_hi:[1,1]
	v_pk_mul_f32 v[100:101], v[100:101], v[186:187] op_sel:[0,1] op_sel_hi:[1,1]
	v_pk_mul_f32 v[106:107], v[106:107], v[110:111]
	v_pk_mul_f32 v[108:109], v[108:109], v[112:113]
	v_pk_mul_f32 v[98:99], v[98:99], v[102:103]
	v_pk_mul_f32 v[100:101], v[100:101], v[104:105]
	v_cvt_pk_bf16_f32 v110, v106, v107
	v_cvt_pk_bf16_f32 v111, v108, v109
	v_cvt_pk_bf16_f32 v112, v98, v99
	v_cvt_pk_bf16_f32 v113, v100, v101
	global_store_dwordx4 v[196:197], v[110:113], off
	v_add_u32_e32 v194, 0x20, v157
	v_mad_i64_i32 v[194:195], s[16:17], v194, s81, v[142:143]
	v_pk_mul_f32 v[90:91], v[94:95], v[90:91]
	v_pk_mul_f32 v[92:93], v[96:97], v[92:93]
	v_pk_mul_f32 v[82:83], v[86:87], v[82:83]
	v_pk_mul_f32 v[84:85], v[88:89], v[84:85]
	v_pk_mul_f32 v[94:95], v[94:95], v[180:181] op_sel_hi:[1,0]
	v_pk_mul_f32 v[96:97], v[96:97], v[180:181] op_sel_hi:[1,0]
	v_pk_mul_f32 v[86:87], v[86:87], v[180:181] op_sel_hi:[1,0]
	v_pk_mul_f32 v[88:89], v[88:89], v[180:181] op_sel_hi:[1,0]
	v_exp_f32_e32 v94, v94
	v_exp_f32_e32 v95, v95
	v_exp_f32_e32 v96, v96
	v_exp_f32_e32 v97, v97
	v_exp_f32_e32 v86, v86
	v_exp_f32_e32 v87, v87
	v_exp_f32_e32 v88, v88
	v_exp_f32_e32 v89, v89
	v_pk_add_f32 v[94:95], v[94:95], v[176:177] op_sel_hi:[1,0]
; __device__ __forceinline__ unsigned cvt_pk_bf16(float lo, float hi) { unsigned r; asm volatile("v_cvt_pk_bf16_f32 %0, %1, %2" : "=v"(r) : "v"(lo), "v"(hi)); return r; }
;     __device__ __forceinline__ void operator()(const f32x4 (&acc)[2][2][4][2], const Unit& u, int wr, int wc, int fr, int fq) const {
;     ...
;             for (int m = 0; m < 4; ++m) {
;                 bf16_t* rowp = O + (size_t)(row0 + ai * HALF + m * 16) * FF + col0;
;                 const float rs = rsv[ai][m];
;                 float a[8];
; #pragma unroll
;                 for (int n = 0; n < 2; ++n)
; #pragma unroll
;                     for (int j = 0; j < 4; ++j) { const float g = acc[ai][0][m][n][j] * rs, up = acc[ai][1][m][n][j] * rs;
;                         const float sg = g * __builtin_amdgcn_rcpf(1.0f + __builtin_amdgcn_exp2f(-1.4426950408889634f * g)); a[n * 4 + j] = sg * up; }
;                 u32x4 w; w.x = cvt_pk_bf16(a[0], a[1]); w.y = cvt_pk_bf16(a[2], a[3]); w.z = cvt_pk_bf16(a[4], a[5]); w.w = cvt_pk_bf16(a[6], a[7]);
;                 *(u32x4*)rowp = w;
;             }
	v_pk_add_f32 v[96:97], v[96:97], v[176:177] op_sel_hi:[1,0]
	v_pk_add_f32 v[86:87], v[86:87], v[176:177] op_sel_hi:[1,0]
	v_pk_add_f32 v[88:89], v[88:89], v[176:177] op_sel_hi:[1,0]
	v_rcp_f32_e32 v94, v94
	v_rcp_f32_e32 v95, v95
	v_rcp_f32_e32 v96, v96
	v_rcp_f32_e32 v97, v97
	v_rcp_f32_e32 v86, v86
	v_rcp_f32_e32 v87, v87
	v_rcp_f32_e32 v88, v88
	v_rcp_f32_e32 v89, v89
	v_pk_mul_f32 v[90:91], v[90:91], v[188:189] op_sel_hi:[1,0]
	v_pk_mul_f32 v[92:93], v[92:93], v[188:189] op_sel_hi:[1,0]
	v_pk_mul_f32 v[82:83], v[82:83], v[188:189] op_sel_hi:[1,0]
	v_pk_mul_f32 v[84:85], v[84:85], v[188:189] op_sel_hi:[1,0]
	v_pk_mul_f32 v[90:91], v[90:91], v[94:95]
	v_pk_mul_f32 v[92:93], v[92:93], v[96:97]
	v_pk_mul_f32 v[82:83], v[82:83], v[86:87]
	v_pk_mul_f32 v[84:85], v[84:85], v[88:89]
	v_cvt_pk_bf16_f32 v94, v90, v91
	v_cvt_pk_bf16_f32 v95, v92, v93
	v_cvt_pk_bf16_f32 v96, v82, v83
	v_cvt_pk_bf16_f32 v97, v84, v85
	global_store_dwordx4 v[194:195], v[94:97], off
	v_add_u32_e32 v196, 0x30, v157
	v_mad_i64_i32 v[196:197], s[16:17], v196, s81, v[142:143]
	v_pk_mul_f32 v[74:75], v[78:79], v[74:75]
	v_pk_mul_f32 v[76:77], v[80:81], v[76:77]
	v_pk_mul_f32 v[66:67], v[70:71], v[66:67]
	v_pk_mul_f32 v[68:69], v[72:73], v[68:69]
	v_pk_mul_f32 v[78:79], v[78:79], v[180:181] op_sel:[0,1] op_sel_hi:[1,1]
	v_pk_mul_f32 v[80:81], v[80:81], v[180:181] op_sel:[0,1] op_sel_hi:[1,1]
	v_pk_mul_f32 v[70:71], v[70:71], v[180:181] op_sel:[0,1] op_sel_hi:[1,1]
	v_pk_mul_f32 v[72:73], v[72:73], v[180:181] op_sel:[0,1] op_sel_hi:[1,1]
	v_exp_f32_e32 v78, v78
	v_exp_f32_e32 v79, v79
	v_exp_f32_e32 v80, v80
	v_exp_f32_e32 v81, v81
	v_exp_f32_e32 v70, v70
	v_exp_f32_e32 v71, v71
	v_exp_f32_e32 v72, v72
	v_exp_f32_e32 v73, v73
	v_pk_add_f32 v[78:79], v[78:79], v[176:177] op_sel_hi:[1,0]
	v_pk_add_f32 v[80:81], v[80:81], v[176:177] op_sel_hi:[1,0]
	v_pk_add_f32 v[70:71], v[70:71], v[176:177] op_sel_hi:[1,0]
	v_pk_add_f32 v[72:73], v[72:73], v[176:177] op_sel_hi:[1,0]
	v_rcp_f32_e32 v78, v78
	v_rcp_f32_e32 v79, v79
	v_rcp_f32_e32 v80, v80
	v_rcp_f32_e32 v81, v81
	v_rcp_f32_e32 v70, v70
	v_rcp_f32_e32 v71, v71
	v_rcp_f32_e32 v72, v72
	v_rcp_f32_e32 v73, v73
	v_pk_mul_f32 v[74:75], v[74:75], v[188:189] op_sel:[0,1] op_sel_hi:[1,1]
	v_pk_mul_f32 v[76:77], v[76:77], v[188:189] op_sel:[0,1] op_sel_hi:[1,1]
	v_pk_mul_f32 v[66:67], v[66:67], v[188:189] op_sel:[0,1] op_sel_hi:[1,1]
	v_pk_mul_f32 v[68:69], v[68:69], v[188:189] op_sel:[0,1] op_sel_hi:[1,1]
	v_pk_mul_f32 v[74:75], v[74:75], v[78:79]
	v_pk_mul_f32 v[76:77], v[76:77], v[80:81]
	v_pk_mul_f32 v[66:67], v[66:67], v[70:71]
	v_pk_mul_f32 v[68:69], v[68:69], v[72:73]
	v_cvt_pk_bf16_f32 v78, v74, v75
	v_cvt_pk_bf16_f32 v79, v76, v77
	v_cvt_pk_bf16_f32 v80, v66, v67
	v_cvt_pk_bf16_f32 v81, v68, v69
	global_store_dwordx4 v[196:197], v[78:81], off
	v_add_u32_e32 v194, 0x80, v157
	v_mad_i64_i32 v[194:195], s[16:17], v194, s81, v[142:143]
	v_pk_mul_f32 v[58:59], v[62:63], v[58:59]
	v_pk_mul_f32 v[60:61], v[64:65], v[60:61]
	v_pk_mul_f32 v[50:51], v[54:55], v[50:51]
	v_pk_mul_f32 v[52:53], v[56:57], v[52:53]
	v_pk_mul_f32 v[62:63], v[62:63], v[182:183] op_sel_hi:[1,0]
	v_pk_mul_f32 v[64:65], v[64:65], v[182:183] op_sel_hi:[1,0]
	v_pk_mul_f32 v[54:55], v[54:55], v[182:183] op_sel_hi:[1,0]
	v_pk_mul_f32 v[56:57], v[56:57], v[182:183] op_sel_hi:[1,0]
	v_exp_f32_e32 v62, v62
	v_exp_f32_e32 v63, v63
	v_exp_f32_e32 v64, v64
	v_exp_f32_e32 v65, v65
	v_exp_f32_e32 v54, v54
	v_exp_f32_e32 v55, v55
	v_exp_f32_e32 v56, v56
	v_exp_f32_e32 v57, v57
	v_pk_add_f32 v[62:63], v[62:63], v[176:177] op_sel_hi:[1,0]
	v_pk_add_f32 v[64:65], v[64:65], v[176:177] op_sel_hi:[1,0]
	v_pk_add_f32 v[54:55], v[54:55], v[176:177] op_sel_hi:[1,0]
	v_pk_add_f32 v[56:57], v[56:57], v[176:177] op_sel_hi:[1,0]
	v_rcp_f32_e32 v62, v62
	v_rcp_f32_e32 v63, v63
	v_rcp_f32_e32 v64, v64
	v_rcp_f32_e32 v65, v65
	v_rcp_f32_e32 v54, v54
	v_rcp_f32_e32 v55, v55
	v_rcp_f32_e32 v56, v56
	v_rcp_f32_e32 v57, v57
	v_pk_mul_f32 v[58:59], v[58:59], v[190:191] op_sel_hi:[1,0]
	v_pk_mul_f32 v[60:61], v[60:61], v[190:191] op_sel_hi:[1,0]
	v_pk_mul_f32 v[50:51], v[50:51], v[190:191] op_sel_hi:[1,0]
	v_pk_mul_f32 v[52:53], v[52:53], v[190:191] op_sel_hi:[1,0]
	v_pk_mul_f32 v[58:59], v[58:59], v[62:63]
	v_pk_mul_f32 v[60:61], v[60:61], v[64:65]
	v_pk_mul_f32 v[50:51], v[50:51], v[54:55]
	v_pk_mul_f32 v[52:53], v[52:53], v[56:57]
	v_cvt_pk_bf16_f32 v62, v58, v59
	v_cvt_pk_bf16_f32 v63, v60, v61
	v_cvt_pk_bf16_f32 v64, v50, v51
	v_cvt_pk_bf16_f32 v65, v52, v53
	global_store_dwordx4 v[194:195], v[62:65], off
	v_add_u32_e32 v196, 0x90, v157
	v_mad_i64_i32 v[196:197], s[16:17], v196, s81, v[142:143]
	v_pk_mul_f32 v[42:43], v[46:47], v[42:43]
	v_pk_mul_f32 v[44:45], v[48:49], v[44:45]
	v_pk_mul_f32 v[34:35], v[38:39], v[34:35]
	v_pk_mul_f32 v[36:37], v[40:41], v[36:37]
	v_pk_mul_f32 v[46:47], v[46:47], v[182:183] op_sel:[0,1] op_sel_hi:[1,1]
	v_pk_mul_f32 v[48:49], v[48:49], v[182:183] op_sel:[0,1] op_sel_hi:[1,1]
	v_pk_mul_f32 v[38:39], v[38:39], v[182:183] op_sel:[0,1] op_sel_hi:[1,1]
; __device__ __forceinline__ unsigned cvt_pk_bf16(float lo, float hi) { unsigned r; asm volatile("v_cvt_pk_bf16_f32 %0, %1, %2" : "=v"(r) : "v"(lo), "v"(hi)); return r; }
;     __device__ __forceinline__ void operator()(const f32x4 (&acc)[2][2][4][2], const Unit& u, int wr, int wc, int fr, int fq) const {
;     ...
;             for (int m = 0; m < 4; ++m) {
;                 bf16_t* rowp = O + (size_t)(row0 + ai * HALF + m * 16) * FF + col0;
;                 const float rs = rsv[ai][m];
;                 float a[8];
; #pragma unroll
;                 for (int n = 0; n < 2; ++n)
; #pragma unroll
;                     for (int j = 0; j < 4; ++j) { const float g = acc[ai][0][m][n][j] * rs, up = acc[ai][1][m][n][j] * rs;
;                         const float sg = g * __builtin_amdgcn_rcpf(1.0f + __builtin_amdgcn_exp2f(-1.4426950408889634f * g)); a[n * 4 + j] = sg * up; }
;                 u32x4 w; w.x = cvt_pk_bf16(a[0], a[1]); w.y = cvt_pk_bf16(a[2], a[3]); w.z = cvt_pk_bf16(a[4], a[5]); w.w = cvt_pk_bf16(a[6], a[7]);
;                 *(u32x4*)rowp = w;
;             }
	v_pk_mul_f32 v[40:41], v[40:41], v[182:183] op_sel:[0,1] op_sel_hi:[1,1]
	v_exp_f32_e32 v46, v46
	v_exp_f32_e32 v47, v47
	v_exp_f32_e32 v48, v48
	v_exp_f32_e32 v49, v49
	v_exp_f32_e32 v38, v38
	v_exp_f32_e32 v39, v39
	v_exp_f32_e32 v40, v40
	v_exp_f32_e32 v41, v41
	v_pk_add_f32 v[46:47], v[46:47], v[176:177] op_sel_hi:[1,0]
	v_pk_add_f32 v[48:49], v[48:49], v[176:177] op_sel_hi:[1,0]
	v_pk_add_f32 v[38:39], v[38:39], v[176:177] op_sel_hi:[1,0]
	v_pk_add_f32 v[40:41], v[40:41], v[176:177] op_sel_hi:[1,0]
	v_rcp_f32_e32 v46, v46
	v_rcp_f32_e32 v47, v47
	v_rcp_f32_e32 v48, v48
	v_rcp_f32_e32 v49, v49
	v_rcp_f32_e32 v38, v38
	v_rcp_f32_e32 v39, v39
	v_rcp_f32_e32 v40, v40
	v_rcp_f32_e32 v41, v41
	v_pk_mul_f32 v[42:43], v[42:43], v[190:191] op_sel:[0,1] op_sel_hi:[1,1]
	v_pk_mul_f32 v[44:45], v[44:45], v[190:191] op_sel:[0,1] op_sel_hi:[1,1]
	v_pk_mul_f32 v[34:35], v[34:35], v[190:191] op_sel:[0,1] op_sel_hi:[1,1]
	v_pk_mul_f32 v[36:37], v[36:37], v[190:191] op_sel:[0,1] op_sel_hi:[1,1]
	v_pk_mul_f32 v[42:43], v[42:43], v[46:47]
	v_pk_mul_f32 v[44:45], v[44:45], v[48:49]
	v_pk_mul_f32 v[34:35], v[34:35], v[38:39]
	v_pk_mul_f32 v[36:37], v[36:37], v[40:41]
	v_cvt_pk_bf16_f32 v46, v42, v43
	v_cvt_pk_bf16_f32 v47, v44, v45
	v_cvt_pk_bf16_f32 v48, v34, v35
	v_cvt_pk_bf16_f32 v49, v36, v37
	global_store_dwordx4 v[196:197], v[46:49], off
	v_add_u32_e32 v194, 0xa0, v157
	v_mad_i64_i32 v[194:195], s[16:17], v194, s81, v[142:143]
	v_pk_mul_f32 v[26:27], v[30:31], v[26:27]
	v_pk_mul_f32 v[28:29], v[32:33], v[28:29]
	v_pk_mul_f32 v[18:19], v[22:23], v[18:19]
	v_pk_mul_f32 v[20:21], v[24:25], v[20:21]
	v_pk_mul_f32 v[30:31], v[30:31], v[184:185] op_sel_hi:[1,0]
	v_pk_mul_f32 v[32:33], v[32:33], v[184:185] op_sel_hi:[1,0]
	v_pk_mul_f32 v[22:23], v[22:23], v[184:185] op_sel_hi:[1,0]
	v_pk_mul_f32 v[24:25], v[24:25], v[184:185] op_sel_hi:[1,0]
	v_exp_f32_e32 v30, v30
	v_exp_f32_e32 v31, v31
	v_exp_f32_e32 v32, v32
	v_exp_f32_e32 v33, v33
	v_exp_f32_e32 v22, v22
	v_exp_f32_e32 v23, v23
	v_exp_f32_e32 v24, v24
	v_exp_f32_e32 v25, v25
	v_pk_add_f32 v[30:31], v[30:31], v[176:177] op_sel_hi:[1,0]
	v_pk_add_f32 v[32:33], v[32:33], v[176:177] op_sel_hi:[1,0]
	v_pk_add_f32 v[22:23], v[22:23], v[176:177] op_sel_hi:[1,0]
	v_pk_add_f32 v[24:25], v[24:25], v[176:177] op_sel_hi:[1,0]
	v_rcp_f32_e32 v30, v30
	v_rcp_f32_e32 v31, v31
	v_rcp_f32_e32 v32, v32
	v_rcp_f32_e32 v33, v33
	v_rcp_f32_e32 v22, v22
	v_rcp_f32_e32 v23, v23
	v_rcp_f32_e32 v24, v24
	v_rcp_f32_e32 v25, v25
	v_pk_mul_f32 v[26:27], v[26:27], v[192:193] op_sel_hi:[1,0]
	v_pk_mul_f32 v[28:29], v[28:29], v[192:193] op_sel_hi:[1,0]
	v_pk_mul_f32 v[18:19], v[18:19], v[192:193] op_sel_hi:[1,0]
	v_pk_mul_f32 v[20:21], v[20:21], v[192:193] op_sel_hi:[1,0]
	v_pk_mul_f32 v[26:27], v[26:27], v[30:31]
	v_pk_mul_f32 v[28:29], v[28:29], v[32:33]
	v_pk_mul_f32 v[18:19], v[18:19], v[22:23]
	v_pk_mul_f32 v[20:21], v[20:21], v[24:25]
	v_cvt_pk_bf16_f32 v30, v26, v27
	v_cvt_pk_bf16_f32 v31, v28, v29
	v_cvt_pk_bf16_f32 v32, v18, v19
	v_cvt_pk_bf16_f32 v33, v20, v21
	global_store_dwordx4 v[194:195], v[30:33], off
	v_add_u32_e32 v196, 0xb0, v157
	v_mad_i64_i32 v[196:197], s[16:17], v196, s81, v[142:143]
	v_pk_mul_f32 v[10:11], v[14:15], v[10:11]
	v_pk_mul_f32 v[12:13], v[16:17], v[12:13]
	v_pk_mul_f32 v[2:3], v[6:7], v[2:3]
	v_pk_mul_f32 v[4:5], v[8:9], v[4:5]
	v_pk_mul_f32 v[14:15], v[14:15], v[184:185] op_sel:[0,1] op_sel_hi:[1,1]
	v_pk_mul_f32 v[16:17], v[16:17], v[184:185] op_sel:[0,1] op_sel_hi:[1,1]
	v_pk_mul_f32 v[6:7], v[6:7], v[184:185] op_sel:[0,1] op_sel_hi:[1,1]
	v_pk_mul_f32 v[8:9], v[8:9], v[184:185] op_sel:[0,1] op_sel_hi:[1,1]
	v_exp_f32_e32 v14, v14
	v_exp_f32_e32 v15, v15
	v_exp_f32_e32 v16, v16
	v_exp_f32_e32 v17, v17
	v_exp_f32_e32 v6, v6
	v_exp_f32_e32 v7, v7
	v_exp_f32_e32 v8, v8
	v_exp_f32_e32 v9, v9
	v_pk_add_f32 v[14:15], v[14:15], v[176:177] op_sel_hi:[1,0]
	v_pk_add_f32 v[16:17], v[16:17], v[176:177] op_sel_hi:[1,0]
	v_pk_add_f32 v[6:7], v[6:7], v[176:177] op_sel_hi:[1,0]
	v_pk_add_f32 v[8:9], v[8:9], v[176:177] op_sel_hi:[1,0]
	v_rcp_f32_e32 v14, v14
	v_rcp_f32_e32 v15, v15
	v_rcp_f32_e32 v16, v16
	v_rcp_f32_e32 v17, v17
	v_rcp_f32_e32 v6, v6
	v_rcp_f32_e32 v7, v7
	v_rcp_f32_e32 v8, v8
	v_rcp_f32_e32 v9, v9
	v_pk_mul_f32 v[10:11], v[10:11], v[192:193] op_sel:[0,1] op_sel_hi:[1,1]
	v_pk_mul_f32 v[12:13], v[12:13], v[192:193] op_sel:[0,1] op_sel_hi:[1,1]
	v_pk_mul_f32 v[2:3], v[2:3], v[192:193] op_sel:[0,1] op_sel_hi:[1,1]
	v_pk_mul_f32 v[4:5], v[4:5], v[192:193] op_sel:[0,1] op_sel_hi:[1,1]
	v_pk_mul_f32 v[10:11], v[10:11], v[14:15]
	v_pk_mul_f32 v[12:13], v[12:13], v[16:17]
	v_pk_mul_f32 v[2:3], v[2:3], v[6:7]
	v_pk_mul_f32 v[4:5], v[4:5], v[8:9]
	v_cvt_pk_bf16_f32 v14, v10, v11
	v_cvt_pk_bf16_f32 v15, v12, v13
	v_cvt_pk_bf16_f32 v16, v2, v3
	v_cvt_pk_bf16_f32 v17, v4, v5
	global_store_dwordx4 v[196:197], v[14:17], off
	s_mov_b64 s[16:17], -1
	s_cbranch_vccnz .LBB0_2270
	s_andn2_b64 vcc, exec, s[4:5]
	s_cbranch_vccnz .LBB0_2269
	s_barrier
	s_branch .LBB0_2269
